# c3sp + exact counted vmcnt waits for the attention K/V staging ds_writes when newer prefetch loads are in flight
# speedup vs baseline: 1.0023x; 1.0023x over previous
; __device__ __forceinline__ unsigned cvt_pk_bf16(float lo, float hi) { unsigned r; asm volatile("v_cvt_pk_bf16_f32 %0, %1, %2" : "=v"(r) : "v"(lo), "v"(hi)); return r; }
; __device__ __forceinline__ void phase_attn(const Params& P, unsigned char* lds) {
;     ...
;                 float pr[16];
; #pragma unroll
;                 for (int i = 0; i < 16; ++i) { const int mk = __builtin_amdgcn_sbfe((int)bits2, (i & 3) + 8 * (i >> 2), 1);
;                     const float e = __builtin_amdgcn_exp2f(__builtin_fmaf(S[i], 0.12751743f, -m));
;                     pr[i] = __int_as_float(__float_as_int(e) & mk); l += pr[i]; }
;                 bf16x8 Pf[2];
; #pragma unroll
;                 for (int s2 = 0; s2 < 2; ++s2) { u32x4 w; w.x = cvt_pk_bf16(pr[8 * s2 + 0], pr[8 * s2 + 1]); w.y = cvt_pk_bf16(pr[8 * s2 + 2], pr[8 * s2 + 3]);
;                     w.z = cvt_pk_bf16(pr[8 * s2 + 4], pr[8 * s2 + 5]); w.w = cvt_pk_bf16(pr[8 * s2 + 6], pr[8 * s2 + 7]); Pf[s2] = __builtin_bit_cast(bf16x8, w); }
;                 const unsigned char* vb = lds + ATT_V_OFF + buf * 20480 + (g * 128 + lr) * 80 + hh * 16;
; #pragma unroll
;                 for (int d = 0; d < 4; ++d)
; #pragma unroll
;                     for (int s2 = 0; s2 < 2; ++s2) { const bf16x8 Vf = *(const bf16x8*)(vb + d * 32 * 80 + s2 * 32); o[d] = __builtin_amdgcn_mfma_f32_32x32x16_bf16(Vf, Pf[s2], o[d], 0, 0, 0); }
;             };
;             ATT_LOAD(sKa, sVa, 0); ATT_STORE(sKa, sVa, 0);
;             if (1 < ntiles) ATT_LOAD(sKb, sVb, 1);
;             __syncthreads();
;             for (int tile = 0; tile < ntiles; tile += 2) {
;                 if (tile + 2 < ntiles) ATT_LOAD(sKa, sVa, tile + 2);
;                 tile_body(tile, 0);
;                 if (tile + 1 < ntiles) ATT_STORE(sKb, sVb, 1);
;                 __syncthreads();
;                 if (tile + 1 >= ntiles) break;
;                 if (tile + 3 < ntiles) ATT_LOAD(sKb, sVb, tile + 3);
;                 tile_body(tile + 1, 1);
;                 if (tile + 2 < ntiles) ATT_STORE(sKa, sVa, 0);
;                 __syncthreads();
.LBB0_822:
	s_waitcnt lgkmcnt(0)
	v_lshrrev_b32_e32 v189, v208, v0
	v_fma_f32 v0, v80, s35, -v188
	v_exp_f32_e32 v0, v0
	v_fma_f32 v3, v81, s35, -v188
	v_exp_f32_e32 v3, v3
	v_bfe_i32 v250, v189, 0, 1
	v_bfe_i32 v251, v189, 1, 1
	v_fma_f32 v5, v83, s35, -v188
	v_and_b32_e32 v0, v0, v250
	v_exp_f32_e32 v5, v5
	v_bfe_i32 v252, v189, 2, 1
	v_and_b32_e32 v2, v3, v251
	v_fma_f32 v3, v82, s35, -v188
	v_exp_f32_e32 v3, v3
	v_bfe_i32 v198, v189, 3, 1
	v_fma_f32 v7, v85, s35, -v188
	v_and_b32_e32 v3, v3, v252
	v_exp_f32_e32 v7, v7
	v_bfe_i32 v250, v189, 8, 1
	v_and_b32_e32 v4, v5, v198
	v_fma_f32 v5, v84, s35, -v188
	v_exp_f32_e32 v5, v5
	v_bfe_i32 v251, v189, 9, 1
	v_fma_f32 v9, v87, s35, -v188
	v_and_b32_e32 v5, v5, v250
	v_exp_f32_e32 v9, v9
	v_bfe_i32 v252, v189, 10, 1
	v_and_b32_e32 v6, v7, v251
	v_fma_f32 v7, v86, s35, -v188
	v_exp_f32_e32 v7, v7
	v_bfe_i32 v198, v189, 11, 1
	v_fma_f32 v11, v89, s35, -v188
	v_and_b32_e32 v7, v7, v252
	v_exp_f32_e32 v11, v11
	v_bfe_i32 v250, v189, 16, 1
	v_and_b32_e32 v8, v9, v198
	v_fma_f32 v9, v88, s35, -v188
	v_exp_f32_e32 v9, v9
	v_bfe_i32 v251, v189, 17, 1
	v_fma_f32 v13, v91, s35, -v188
	v_and_b32_e32 v9, v9, v250
	v_exp_f32_e32 v13, v13
	v_bfe_i32 v252, v189, 18, 1
	v_and_b32_e32 v10, v11, v251
	v_fma_f32 v11, v90, s35, -v188
	v_exp_f32_e32 v11, v11
	v_bfe_i32 v198, v189, 19, 1
	v_fma_f32 v15, v93, s35, -v188
	v_and_b32_e32 v11, v11, v252
	v_exp_f32_e32 v15, v15
	v_bfe_i32 v250, v189, 24, 1
	v_and_b32_e32 v12, v13, v198
	v_fma_f32 v13, v92, s35, -v188
	v_exp_f32_e32 v13, v13
	v_bfe_i32 v251, v189, 25, 1
	v_fma_f32 v81, v95, s35, -v188
	v_and_b32_e32 v13, v13, v250
	v_exp_f32_e32 v81, v81
	v_bfe_i32 v252, v189, 26, 1
	v_and_b32_e32 v14, v15, v251
	v_fma_f32 v15, v94, s35, -v188
	v_exp_f32_e32 v15, v15
	v_bfe_i32 v198, v189, 27, 1
	v_cvt_pk_bf16_f32 v82, v0, v2
	v_cvt_pk_bf16_f32 v83, v3, v4
	v_cvt_pk_bf16_f32 v84, v5, v6
	v_cvt_pk_bf16_f32 v85, v7, v8
	s_nop 0
	v_and_b32_e32 v15, v15, v252
	v_cvt_pk_bf16_f32 v86, v9, v10
	v_cvt_pk_bf16_f32 v87, v11, v12
	v_cvt_pk_bf16_f32 v88, v13, v14
	s_add_i32 s6, s11, -2
	s_cmp_lt_i32 s6, s38
	v_and_b32_e32 v80, v81, v198
	v_cvt_pk_bf16_f32 v89, v15, v80
	s_nop 1
	v_mfma_f32_32x32x16_bf16 v[64:79], v[190:193], v[82:85], v[64:79]
	s_cselect_b64 s[8:9], -1, 0
	s_cmp_ge_i32 s6, s38
	v_mfma_f32_32x32x16_bf16 v[64:79], v[194:197], v[86:89], v[64:79]
	v_mfma_f32_32x32x16_bf16 v[48:63], v[226:229], v[82:85], v[48:63]
	v_mfma_f32_32x32x16_bf16 v[48:63], v[230:233], v[86:89], v[48:63]
	v_mfma_f32_32x32x16_bf16 v[32:47], v[234:237], v[82:85], v[32:47]
	v_mfma_f32_32x32x16_bf16 v[32:47], v[238:241], v[86:89], v[32:47]
	v_mfma_f32_32x32x16_bf16 v[16:31], v[242:245], v[82:85], v[16:31]
	v_mfma_f32_32x32x16_bf16 v[16:31], v[246:249], v[86:89], v[16:31]
	s_cbranch_scc1 .LBB0_824
	s_cmp_lg_u64 s[0:1], 0
	s_cbranch_scc1 .Latt_w1_new
	s_waitcnt vmcnt(3)
	ds_write_b128 v215, v[132:135] offset:16384
	s_waitcnt vmcnt(2)
	ds_write_b128 v216, v[140:143] offset:53248
	s_waitcnt vmcnt(1)
	ds_write_b128 v215, v[148:151] offset:24576
	s_waitcnt vmcnt(0)
	ds_write_b128 v216, v[156:159] offset:63488
	s_branch .LBB0_824
.Latt_w1_new:
	s_waitcnt vmcnt(7)
	ds_write_b128 v215, v[132:135] offset:16384
	s_waitcnt vmcnt(6)
	ds_write_b128 v216, v[140:143] offset:53248
	s_waitcnt vmcnt(5)
	ds_write_b128 v215, v[148:151] offset:24576
	s_waitcnt vmcnt(4)
	ds_write_b128 v216, v[156:159] offset:63488
.LBB0_824:
	v_add_f32_e32 v0, v183, v0
	v_add_f32_e32 v0, v2, v0
	v_add_f32_e32 v0, v3, v0
	v_add_f32_e32 v0, v4, v0
	v_add_f32_e32 v0, v5, v0
	v_add_f32_e32 v0, v6, v0
	v_add_f32_e32 v0, v7, v0
	v_add_f32_e32 v0, v8, v0
	v_add_f32_e32 v0, v9, v0
	v_add_f32_e32 v0, v10, v0
	v_add_f32_e32 v0, v11, v0
	v_add_f32_e32 v0, v12, v0
	v_add_f32_e32 v0, v13, v0
	v_add_f32_e32 v0, v14, v0
	v_add_f32_e32 v0, v15, v0
	v_add_f32_e32 v183, v80, v0
	s_mov_b64 s[6:7], -1
	s_andn2_b64 vcc, exec, s[8:9]
	v_readfirstlane_b32 s8, v0
	s_waitcnt lgkmcnt(0)
	s_barrier
	s_cbranch_vccnz .LBB0_829
	s_cmp_ge_i32 s11, s38
	s_cselect_b32 s97, 1, 0
	s_cbranch_scc1 .LBB0_827
	v_min_u32_e32 v0, 0x80f, v186
	v_add_u32_e32 v0, s10, v0
	v_mul_i32_i24_e32 v2, 0x1600, v0
	v_ashrrev_i32_e32 v3, 31, v2
	v_lshl_add_u64 v[2:3], v[178:179], 0, v[2:3]
	v_min_u32_e32 v0, 0x7ff, v186
	global_load_dwordx4 v[132:135], v[2:3], off offset:2048
	v_add_co_u32_e32 v2, vcc, 0xffffe000, v184
	v_or_b32_e32 v0, s73, v0
	s_nop 0
	v_addc_co_u32_e32 v3, vcc, -1, v185, vcc
	v_mul_u32_u24_e32 v0, 0x1600, v0
	global_load_dwordx4 v[140:143], v[2:3], off
	v_lshl_add_u64 v[2:3], v[178:179], 0, v[0:1]
	global_load_dwordx4 v[148:151], v[2:3], off offset:2048
	global_load_dwordx4 v[156:159], v[184:185], off

; __device__ __forceinline__ unsigned cvt_pk_bf16(float lo, float hi) { unsigned r; asm volatile("v_cvt_pk_bf16_f32 %0, %1, %2" : "=v"(r) : "v"(lo), "v"(hi)); return r; }
; __device__ __forceinline__ void phase_attn(const Params& P, unsigned char* lds) {
;     ...
;                 float pr[16];
; #pragma unroll
;                 for (int i = 0; i < 16; ++i) { const int mk = __builtin_amdgcn_sbfe((int)bits2, (i & 3) + 8 * (i >> 2), 1);
;                     const float e = __builtin_amdgcn_exp2f(__builtin_fmaf(S[i], 0.12751743f, -m));
;                     pr[i] = __int_as_float(__float_as_int(e) & mk); l += pr[i]; }
;                 bf16x8 Pf[2];
; #pragma unroll
;                 for (int s2 = 0; s2 < 2; ++s2) { u32x4 w; w.x = cvt_pk_bf16(pr[8 * s2 + 0], pr[8 * s2 + 1]); w.y = cvt_pk_bf16(pr[8 * s2 + 2], pr[8 * s2 + 3]);
;                     w.z = cvt_pk_bf16(pr[8 * s2 + 4], pr[8 * s2 + 5]); w.w = cvt_pk_bf16(pr[8 * s2 + 6], pr[8 * s2 + 7]); Pf[s2] = __builtin_bit_cast(bf16x8, w); }
;                 const unsigned char* vb = lds + ATT_V_OFF + buf * 20480 + (g * 128 + lr) * 80 + hh * 16;
; #pragma unroll
;                 for (int d = 0; d < 4; ++d)
; #pragma unroll
;                     for (int s2 = 0; s2 < 2; ++s2) { const bf16x8 Vf = *(const bf16x8*)(vb + d * 32 * 80 + s2 * 32); o[d] = __builtin_amdgcn_mfma_f32_32x32x16_bf16(Vf, Pf[s2], o[d], 0, 0, 0); }
;             };
;             ATT_LOAD(sKa, sVa, 0); ATT_STORE(sKa, sVa, 0);
;             if (1 < ntiles) ATT_LOAD(sKb, sVb, 1);
;             __syncthreads();
;             for (int tile = 0; tile < ntiles; tile += 2) {
;                 if (tile + 2 < ntiles) ATT_LOAD(sKa, sVa, tile + 2);
;                 tile_body(tile, 0);
;                 if (tile + 1 < ntiles) ATT_STORE(sKb, sVb, 1);
;                 __syncthreads();
;                 if (tile + 1 >= ntiles) break;
;                 if (tile + 3 < ntiles) ATT_LOAD(sKb, sVb, tile + 3);
;                 tile_body(tile + 1, 1);
;                 if (tile + 2 < ntiles) ATT_STORE(sKa, sVa, 0);
;                 __syncthreads();
.LBB0_831:
	s_waitcnt lgkmcnt(0)
	v_lshrrev_b32_e32 v189, v208, v0
	v_fmamk_f32 v0, v80, 0x3e0293ee, v7
	v_exp_f32_e32 v0, v0
	v_fmamk_f32 v3, v81, 0x3e0293ee, v7
	v_exp_f32_e32 v3, v3
	v_bfe_i32 v250, v189, 0, 1
	v_bfe_i32 v251, v189, 1, 1
	v_fmamk_f32 v5, v83, 0x3e0293ee, v7
	v_and_b32_e32 v0, v0, v250
	v_exp_f32_e32 v5, v5
	v_bfe_i32 v252, v189, 2, 1
	v_and_b32_e32 v2, v3, v251
	v_fmamk_f32 v3, v82, 0x3e0293ee, v7
	v_exp_f32_e32 v3, v3
	v_bfe_i32 v198, v189, 3, 1
	v_fmamk_f32 v8, v85, 0x3e0293ee, v7
	v_and_b32_e32 v3, v3, v252
	v_exp_f32_e32 v8, v8
	v_bfe_i32 v250, v189, 8, 1
	v_and_b32_e32 v4, v5, v198
	v_fmamk_f32 v5, v84, 0x3e0293ee, v7
	v_exp_f32_e32 v5, v5
	v_bfe_i32 v251, v189, 9, 1
	v_fmamk_f32 v10, v87, 0x3e0293ee, v7
	v_and_b32_e32 v5, v5, v250
	v_exp_f32_e32 v10, v10
	v_bfe_i32 v252, v189, 10, 1
	v_and_b32_e32 v6, v8, v251
	v_fmamk_f32 v8, v86, 0x3e0293ee, v7
	v_exp_f32_e32 v8, v8
	v_bfe_i32 v198, v189, 11, 1
	v_fmamk_f32 v12, v89, 0x3e0293ee, v7
	v_and_b32_e32 v8, v8, v252
	v_exp_f32_e32 v12, v12
	v_bfe_i32 v250, v189, 16, 1
	v_and_b32_e32 v9, v10, v198
	v_fmamk_f32 v10, v88, 0x3e0293ee, v7
	v_exp_f32_e32 v10, v10
	v_bfe_i32 v251, v189, 17, 1
	v_fmamk_f32 v14, v91, 0x3e0293ee, v7
	v_and_b32_e32 v10, v10, v250
	v_exp_f32_e32 v14, v14
	v_bfe_i32 v252, v189, 18, 1
	v_and_b32_e32 v11, v12, v251
	v_fmamk_f32 v12, v90, 0x3e0293ee, v7
	v_exp_f32_e32 v12, v12
	v_bfe_i32 v198, v189, 19, 1
	v_fmamk_f32 v80, v93, 0x3e0293ee, v7
	v_and_b32_e32 v12, v12, v252
	v_exp_f32_e32 v80, v80
	v_bfe_i32 v250, v189, 24, 1
	v_and_b32_e32 v13, v14, v198
	v_fmamk_f32 v14, v92, 0x3e0293ee, v7
	v_exp_f32_e32 v14, v14
	v_bfe_i32 v251, v189, 25, 1
	v_bfe_i32 v252, v189, 26, 1
	v_and_b32_e32 v14, v14, v250
	s_nop 1
	v_and_b32_e32 v15, v80, v251
	v_fmamk_f32 v80, v94, 0x3e0293ee, v7
	v_exp_f32_e32 v80, v80
	v_fmac_f32_e32 v7, 0x3e0293ee, v95
	v_exp_f32_e32 v82, v7
	s_nop 1
	v_and_b32_e32 v7, v80, v252
	v_bfe_i32 v198, v189, 27, 1
	s_nop 1
	v_and_b32_e32 v80, v82, v198
	v_cvt_pk_bf16_f32 v82, v0, v2
	v_cvt_pk_bf16_f32 v83, v3, v4
	v_cvt_pk_bf16_f32 v84, v5, v6
	v_cvt_pk_bf16_f32 v85, v8, v9
	v_cvt_pk_bf16_f32 v86, v10, v11
	v_cvt_pk_bf16_f32 v87, v12, v13
	v_cvt_pk_bf16_f32 v88, v14, v15
	v_cvt_pk_bf16_f32 v89, v7, v80
	s_nop 1
	v_mfma_f32_32x32x16_bf16 v[64:79], v[190:193], v[82:85], v[64:79]
	s_andn2_b64 vcc, exec, s[0:1]
	v_mfma_f32_32x32x16_bf16 v[64:79], v[194:197], v[86:89], v[64:79]
	v_mfma_f32_32x32x16_bf16 v[48:63], v[226:229], v[82:85], v[48:63]
	v_mfma_f32_32x32x16_bf16 v[48:63], v[230:233], v[86:89], v[48:63]
	v_mfma_f32_32x32x16_bf16 v[32:47], v[234:237], v[82:85], v[32:47]
	v_mfma_f32_32x32x16_bf16 v[32:47], v[238:241], v[86:89], v[32:47]
	v_mfma_f32_32x32x16_bf16 v[16:31], v[242:245], v[82:85], v[16:31]
	v_mfma_f32_32x32x16_bf16 v[16:31], v[246:249], v[86:89], v[16:31]
	s_cbranch_vccnz .LBB0_817
	s_cmp_eq_u32 s97, 0
	s_cbranch_scc1 .Latt_w2_new
	s_waitcnt vmcnt(3)
	ds_write_b128 v215, v[128:131]
	s_waitcnt vmcnt(2)
	ds_write_b128 v216, v[136:139] offset:32768
	s_waitcnt vmcnt(1)
	ds_write_b128 v215, v[144:147] offset:8192
	s_waitcnt vmcnt(0)
	ds_write_b128 v216, v[152:155] offset:43008
	s_branch .LBB0_817
.Latt_w2_new:
	s_waitcnt vmcnt(7)
	ds_write_b128 v215, v[128:131]
	s_waitcnt vmcnt(6)
	ds_write_b128 v216, v[136:139] offset:32768
	s_waitcnt vmcnt(5)
	ds_write_b128 v215, v[144:147] offset:8192
	s_waitcnt vmcnt(4)
	ds_write_b128 v216, v[152:155] offset:43008
	s_branch .LBB0_817
